# v36 + nt on phase 4's read-once raw q/k/v row loads (rows are overwritten in place afterwards)
# baseline (speedup 1.0000x reference)
.LBB0_1403:
	v_add_u32_e32 v2, s4, v202
	v_cmp_gt_i32_e32 vcc, s70, v2
	v_mov_b32_e32 v68, 0
	v_mov_b32_e32 v72, 0
	v_mov_b32_e32 v73, 0
	v_mov_b32_e32 v74, 0
	v_mov_b32_e32 v75, 0
	v_mov_b32_e32 v76, 0
	v_mov_b32_e32 v77, 0
	v_mov_b32_e32 v78, 0
	v_mov_b32_e32 v79, 0
	s_and_saveexec_b64 s[4:5], vcc
	s_cbranch_execz .LBB0_1405
	v_add_u32_e32 v70, s16, v2
	v_ashrrev_i32_e32 v71, 31, v70
	v_lshlrev_b64 v[70:71], 11, v[70:71]
	v_lshl_add_u64 v[70:71], v[184:185], 0, v[70:71]
	global_load_dwordx4 v[72:75], v[70:71], off offset:16 nt
	global_load_dwordx4 v[76:79], v[70:71], off nt
.LBB0_1405:
	s_or_b64 exec, exec, s[4:5]
	v_add_u32_e32 v84, 8, v2
	v_cmp_gt_i32_e32 vcc, s70, v84
	v_mov_b32_e32 v69, 0
	v_mov_b32_e32 v70, 0
	v_mov_b32_e32 v71, 0
	v_mov_b32_e32 v80, 0
	v_mov_b32_e32 v81, 0
	v_mov_b32_e32 v82, 0
	v_mov_b32_e32 v83, 0
	s_and_saveexec_b64 s[4:5], vcc
	s_cbranch_execz .LBB0_1407
	v_add_u32_e32 v68, s16, v84
	v_ashrrev_i32_e32 v69, 31, v68
	v_lshlrev_b64 v[68:69], 11, v[68:69]
	v_lshl_add_u64 v[80:81], v[184:185], 0, v[68:69]
	global_load_dwordx4 v[68:71], v[80:81], off offset:16 nt
	s_nop 0
	global_load_dwordx4 v[80:83], v[80:81], off nt
.LBB0_1407:
	s_or_b64 exec, exec, s[4:5]
	v_add_u32_e32 v85, 16, v2
	v_cmp_gt_i32_e32 vcc, s70, v85
	v_mov_b32_e32 v84, 0
	v_mov_b32_e32 v88, 0
	v_mov_b32_e32 v89, 0
	v_mov_b32_e32 v90, 0
	v_mov_b32_e32 v91, 0
	v_mov_b32_e32 v92, 0
	v_mov_b32_e32 v93, 0
	v_mov_b32_e32 v94, 0
	v_mov_b32_e32 v95, 0
	s_and_saveexec_b64 s[4:5], vcc
	s_cbranch_execz .LBB0_1409
	v_add_u32_e32 v86, s16, v85
	v_ashrrev_i32_e32 v87, 31, v86
	v_lshlrev_b64 v[86:87], 11, v[86:87]
	v_lshl_add_u64 v[86:87], v[184:185], 0, v[86:87]
	global_load_dwordx4 v[88:91], v[86:87], off offset:16 nt
	global_load_dwordx4 v[92:95], v[86:87], off nt
.LBB0_1409:
	s_or_b64 exec, exec, s[4:5]
	v_add_u32_e32 v100, 24, v2
	v_cmp_gt_i32_e32 vcc, s70, v100
	v_mov_b32_e32 v85, 0
	v_mov_b32_e32 v86, 0
	v_mov_b32_e32 v87, 0
	v_mov_b32_e32 v96, 0
	v_mov_b32_e32 v97, 0
	v_mov_b32_e32 v98, 0
	v_mov_b32_e32 v99, 0
	s_and_saveexec_b64 s[4:5], vcc
	s_cbranch_execz .LBB0_1402
	v_add_u32_e32 v84, s16, v100
	v_ashrrev_i32_e32 v85, 31, v84
	v_lshlrev_b64 v[84:85], 11, v[84:85]
	v_lshl_add_u64 v[96:97], v[184:185], 0, v[84:85]
	global_load_dwordx4 v[84:87], v[96:97], off offset:16 nt
	s_nop 0
	global_load_dwordx4 v[96:99], v[96:97], off nt
	s_branch .LBB0_1402

.LBB0_1461:
	v_mad_i64_i32 v[134:135], s[14:15], v2, s69, v[186:187]
	global_load_dwordx4 v[136:139], v[134:135], off offset:16 nt
	global_load_dwordx4 v[140:143], v[134:135], off nt
	s_andn2_saveexec_b64 s[12:13], s[12:13]
	s_cbranch_execnz .LBB0_1422
	s_branch .LBB0_1423
.LBB0_1462:
	v_add_u32_e32 v132, 1, v2
	v_mad_i64_i32 v[144:145], s[14:15], v132, s69, v[186:187]
	global_load_dwordx4 v[132:135], v[144:145], off offset:16 nt
	s_nop 0
	global_load_dwordx4 v[144:147], v[144:145], off nt
	s_andn2_saveexec_b64 s[12:13], s[12:13]
	s_cbranch_execnz .LBB0_1433
	s_branch .LBB0_1434
.LBB0_1463:
	v_add_u32_e32 v149, 2, v2
	v_mad_i64_i32 v[150:151], s[14:15], v149, s69, v[186:187]
	global_load_dwordx4 v[152:155], v[150:151], off offset:16 nt
	global_load_dwordx4 v[156:159], v[150:151], off nt
	s_andn2_saveexec_b64 s[12:13], s[12:13]
	s_cbranch_execnz .LBB0_1444
	s_branch .LBB0_1445
.LBB0_1464:
	v_add_u32_e32 v2, 3, v2
	v_mad_i64_i32 v[160:161], s[14:15], v2, s69, v[186:187]
	global_load_dwordx4 v[148:151], v[160:161], off offset:16 nt
	s_nop 0
	global_load_dwordx4 v[160:163], v[160:161], off nt
	s_andn2_saveexec_b64 s[12:13], s[12:13]
	s_cbranch_execnz .LBB0_1455
	s_branch .LBB0_1456
